# b11 + fine workgroup stagger (8 groups x 1.8us) at INB/OUTPROJ/KVQG/WO starts to spread L2 channel access for 2KB-pitch operands
# baseline (speedup 1.0000x reference)
.LBB0_270:
	s_lshr_b32 s98, s33, 3
	s_and_b32 s98, s98, 7
	s_mul_i32 s98, s98, 180
	s_memrealtime s[100:101]
	s_waitcnt lgkmcnt(0)
	s_add_u32 s99, s100, s98
.Lfa_skew0:
	s_sleep 2
	s_memrealtime s[100:101]
	s_waitcnt lgkmcnt(0)
	s_sub_u32 s101, s100, s99
	s_cmp_lt_i32 s101, 0
	s_cbranch_scc1 .Lfa_skew0
	s_cmp_lt_i32 s46, 4
	s_cselect_b64 s[4:5], -1, 0
	s_add_u32 s26, s44, 0x21800000
	s_addc_u32 s27, s45, 0
	s_and_b64 s[4:5], s[4:5], s[2:3]
	s_andn2_b64 vcc, exec, s[4:5]
	s_cbranch_vccnz .LBB0_291
	v_mov_b32_e32 v8, v188
	s_cmpk_gt_i32 s33, 0x3ff
	v_readfirstlane_b32 s40, v8
	s_cbranch_scc1 .LBB0_291
	s_ashr_i32 s41, s33, 31
	s_lshr_b32 s2, s41, 29
	s_add_i32 s7, s33, s2
	s_and_b32 s2, s7, -8
	s_sub_i32 s8, s33, s2
	s_cmp_gt_i32 s8, -1
	s_cbranch_scc0 .LBB0_274
	s_lshl_b32 s6, s8, 7
	s_cbranch_execz .LBB0_275
	s_branch .LBB0_276

.Lfa_skew1:
	s_sleep 2
	s_memrealtime s[100:101]
	s_waitcnt lgkmcnt(0)
	s_sub_u32 s101, s100, s99
	s_cmp_lt_i32 s101, 0
	s_cbranch_scc1 .Lfa_skew1
	s_cmp_lt_i32 s46, 5
	s_cselect_b64 s[2:3], -1, 0
	s_add_u32 s74, s44, 0x37040000
	s_addc_u32 s75, s45, 0
	s_and_b64 s[0:1], s[2:3], s[0:1]
	s_andn2_b64 vcc, exec, s[0:1]
	s_cbranch_vccnz .LBB0_384
	v_mov_b32_e32 v8, v188
	s_cmpk_lt_i32 s33, 0x400
	s_cselect_b64 s[2:3], -1, 0
	s_cmpk_gt_i32 s33, 0x3ff
	v_readfirstlane_b32 s30, v8
	s_cbranch_scc1 .LBB0_352
	s_ashr_i32 s4, s33, 31
	s_lshr_b32 s4, s4, 29
	s_add_i32 s6, s33, s4
	s_and_b32 s4, s6, -8
	s_sub_i32 s7, s33, s4
	s_cmp_gt_i32 s7, -1
	s_cbranch_scc0 .LBB0_349
	s_lshl_b32 s8, s7, 7
	s_cbranch_execz .LBB0_350
	s_branch .LBB0_351

.Lfa_skew2:
	s_sleep 2
	s_memrealtime s[100:101]
	s_waitcnt lgkmcnt(0)
	s_sub_u32 s101, s100, s99
	s_cmp_lt_i32 s101, 0
	s_cbranch_scc1 .Lfa_skew2
	s_cmp_lt_i32 s46, 8
	s_cselect_b64 s[2:3], -1, 0
	s_and_b64 s[0:1], s[2:3], s[0:1]
	s_andn2_b64 vcc, exec, s[0:1]
	s_cbranch_vccnz .LBB0_795
	v_mov_b32_e32 v10, v188
	s_cmpk_lt_i32 s33, 0xb00
	s_cselect_b64 s[2:3], -1, 0
	s_cmpk_gt_i32 s33, 0xaff
	v_readfirstlane_b32 s19, v10
	s_cbranch_scc1 .LBB0_631
	s_ashr_i32 s4, s33, 31
	s_lshr_b32 s4, s4, 29
	s_add_i32 s4, s33, s4
	s_ashr_i32 s5, s4, 3
	s_and_b32 s4, s4, -8
	s_sub_i32 s4, s33, s4
	s_cmp_lt_i32 s4, 0
	s_movk_i32 s6, 0x161
	s_cselect_b32 s6, s6, 0x160
	s_mul_i32 s4, s4, s6
	s_add_i32 s4, s4, s5
	s_mul_hi_i32 s5, s4, 0x2e8ba2e9
	s_lshr_b32 s6, s5, 31
	s_ashr_i32 s5, s5, 4
	s_add_i32 s5, s5, s6
	s_lshl_b32 s6, s5, 3
	s_mulk_i32 s5, 0x58
	s_sub_i32 s4, s4, s5
	s_bfe_i32 s5, s4, 0x80000
	s_bfe_u32 s5, s5, 0x3000c
	s_add_i32 s5, s4, s5
	s_bfe_i32 s7, s5, 0x80000
	s_and_b32 s5, s5, 0xf8
	s_sub_i32 s4, s4, s5
	s_sext_i32_i16 s7, s7
	s_sext_i32_i8 s4, s4
	s_add_i32 s36, s6, s4
	s_ashr_i32 s14, s7, 3

.Lfa_skew3:
	s_sleep 2
	s_memrealtime s[100:101]
	s_waitcnt lgkmcnt(0)
	s_sub_u32 s101, s100, s99
	s_cmp_lt_i32 s101, 0
	s_cbranch_scc1 .Lfa_skew3
	s_cmp_lt_i32 s46, 12
	s_cselect_b64 s[2:3], -1, 0
	s_and_b64 s[0:1], s[2:3], s[0:1]
	s_andn2_b64 vcc, exec, s[0:1]
	s_cbranch_vccnz .LBB0_1571
	v_mov_b32_e32 v8, v188
	s_cmpk_lt_i32 s33, 0x400
	s_cselect_b64 s[2:3], -1, 0
	s_cmpk_gt_i32 s33, 0x3ff
	v_readfirstlane_b32 s30, v8
	s_cbranch_scc1 .LBB0_1539
	s_ashr_i32 s4, s33, 31
	s_lshr_b32 s4, s4, 29
	s_add_i32 s6, s33, s4
	s_and_b32 s4, s6, -8
	s_sub_i32 s7, s33, s4
	s_cmp_gt_i32 s7, -1
	s_cbranch_scc0 .LBB0_1536
	s_lshl_b32 s8, s7, 7
	s_cbranch_execz .LBB0_1537
	s_branch .LBB0_1538
